# DeltaNet scan rewritten by hand: role-split waves (2 compute + 4 staging), quad-transposed dwordx4 stores, scan spread over 16 workgroups (2 per b,head) to lift per-CU load bandwidth bound
# speedup vs baseline: 1.0441x; 1.0441x over previous
.LBB0_1086:
	s_andn2_b64 vcc, exec, s[2:3]
	s_cbranch_vccnz .LBB0_1445
	s_mov_b64 s[2:3], s[40:41]
	v_mov_b32_e32 v96, v160
	s_waitcnt vmcnt(0) lgkmcnt(0)
	v_mov_b64_e32 v[10:11], s[2:3]
	flat_load_dwordx2 v[8:9], v[10:11] offset:64
	flat_load_dwordx4 v[4:7], v[10:11] offset:144
	s_waitcnt vmcnt(0) lgkmcnt(0)
	flat_load_dwordx4 v[0:3], v[10:11] offset:240
	flat_load_dwordx2 v[80:81], v[10:11] offset:160
	v_readlane_b32 s2, v253, 0
	s_cmp_gt_i32 s2, 15
	s_mov_b64 s[2:3], -1
	s_cbranch_scc0 .LBB0_1376
	v_readlane_b32 s2, v253, 0
	s_add_i32 s95, s2, -16
	s_cmpk_gt_i32 s2, 0x417
	s_mov_b64 s[2:3], 0xc180000
	s_waitcnt vmcnt(0) lgkmcnt(0)
	v_lshl_add_u64 v[82:83], v[2:3], 0, s[2:3]
	s_cbranch_scc1 .LBB0_1110
	s_mov_b64 s[2:3], 0x152a0000
	v_lshl_add_u64 v[84:85], v[2:3], 0, s[2:3]
	v_readlane_b32 s2, v255, 24
	s_lshl_b32 s2, s2, 6
	s_ashr_i32 s3, s2, 31
	v_lshl_add_u64 v[86:87], s[2:3], 2, v[8:9]
	s_branch .LBB0_1092

.LBB0_1091:
	v_and_b32_e32 v25, 0x70, v194
	v_mov_b32_e32 v33, v163
	v_add_u32_e32 v44, 16, v25
	v_ashrrev_i32_e32 v25, 31, v24
	v_lshl_add_u64 v[32:33], s[2:3], 0, v[32:33]
	v_lshlrev_b32_e32 v162, 2, v97
	v_lshl_add_u64 v[32:33], v[32:33], 0, v[24:25]
	v_lshl_add_u64 v[24:25], v[86:87], 0, v[162:163]
	global_load_dword v46, v[24:25], off
	v_mov_b32_e32 v31, v163
	v_mov_b32_e32 v29, v163
	v_lshl_add_u64 v[34:35], v[30:31], 2, v[86:87]
	global_load_dword v48, v[34:35], off
	v_lshl_add_u64 v[24:25], v[28:29], 2, v[86:87]
	global_load_dword v47, v[24:25], off
	v_mov_b32_e32 v27, v163
	v_lshl_add_u64 v[38:39], v[26:27], 2, v[86:87]
	global_load_dword v49, v[38:39], off
	v_xor_b32_e32 v38, 1, v194
	v_cmp_lt_i32_e32 vcc, v38, v44
	v_mov_b32_e32 v34, v8
	v_mov_b32_e32 v35, v12
	v_cndmask_b32_e32 v38, v194, v38, vcc
	v_lshlrev_b32_e32 v50, 2, v38
	v_xor_b32_e32 v38, 2, v194
	v_cmp_lt_i32_e32 vcc, v38, v44
	v_mov_b32_e32 v39, v13
	v_pk_mul_f32 v[34:35], v[34:35], v[34:35]
	v_cndmask_b32_e32 v45, v194, v38, vcc
	v_mov_b32_e32 v38, v9
	v_mov_b32_e32 v36, v16
	v_mov_b32_e32 v37, v20
	v_pk_mul_f32 v[38:39], v[38:39], v[38:39]
	v_mov_b32_e32 v40, v17
	v_mov_b32_e32 v41, v21
	v_pk_mul_f32 v[36:37], v[36:37], v[36:37]
	v_pk_mul_f32 v[40:41], v[40:41], v[40:41]
	v_mov_b32_e32 v42, v38
	v_mov_b32_e32 v43, v34
	v_mov_b32_e32 v34, v39
	v_pk_add_f32 v[34:35], v[42:43], v[34:35]
	v_mov_b32_e32 v38, v40
	v_mov_b32_e32 v39, v36
	v_pk_add_f32 v[34:35], v[34:35], v[38:39]
	v_mov_b32_e32 v36, v41
	v_pk_add_f32 v[34:35], v[34:35], v[36:37]
	ds_bpermute_b32 v37, v50, v35
	ds_bpermute_b32 v36, v50, v34
	v_lshlrev_b32_e32 v51, 2, v45
	v_xor_b32_e32 v38, 4, v194
	v_cmp_lt_i32_e32 vcc, v38, v44
	v_readlane_b32 s2, v254, 44
	s_waitcnt lgkmcnt(0)
	v_pk_add_f32 v[34:35], v[34:35], v[36:37]
	ds_bpermute_b32 v37, v51, v35
	ds_bpermute_b32 v36, v51, v34
	v_cndmask_b32_e32 v38, v194, v38, vcc
	v_lshlrev_b32_e32 v52, 2, v38
	v_xor_b32_e32 v38, 8, v194
	v_cmp_lt_i32_e32 vcc, v38, v44
	s_waitcnt lgkmcnt(0)
	v_pk_add_f32 v[34:35], v[34:35], v[36:37]
	ds_bpermute_b32 v37, v52, v35
	ds_bpermute_b32 v36, v52, v34
	v_cndmask_b32_e32 v38, v194, v38, vcc
	v_lshlrev_b32_e32 v53, 2, v38
	v_readlane_b32 s3, v254, 45
	s_mov_b32 s2, 0x358637bd
	s_waitcnt lgkmcnt(0)
	v_pk_add_f32 v[34:35], v[34:35], v[36:37]
	ds_bpermute_b32 v37, v53, v35
	ds_bpermute_b32 v36, v53, v34
	s_mov_b32 s89, s3
	v_lshl_add_u64 v[24:25], v[84:85], 0, s[88:89]
	v_lshlrev_b64 v[32:33], 11, v[32:33]
	v_lshl_add_u64 v[38:39], v[24:25], 0, v[32:33]
	s_waitcnt lgkmcnt(0)
	v_pk_add_f32 v[34:35], v[34:35], v[36:37]
	v_mov_b64_e32 v[36:37], s[2:3]
	s_mov_b32 s2, 0x3c800000
	v_pk_fma_f32 v[34:35], v[34:35], s[2:3], v[36:37] op_sel_hi:[1,0,0]
	v_lshlrev_b32_e32 v162, 1, v97
	v_mul_f32_e32 v44, 0x4b800000, v35
	v_cmp_gt_f32_e32 vcc, s90, v35
	v_lshl_add_u64 v[40:41], v[38:39], 0, v[162:163]
	v_lshlrev_b64 v[28:29], 1, v[28:29]
	v_cndmask_b32_e32 v35, v35, v44, vcc
	v_rsq_f32_e32 v35, v35
	v_lshl_add_u64 v[42:43], v[38:39], 0, v[28:29]
	v_lshlrev_b64 v[30:31], 1, v[30:31]
	v_lshl_add_u64 v[44:45], v[38:39], 0, v[30:31]
	v_mul_f32_e32 v54, 0x45800000, v35
	v_cndmask_b32_e32 v35, v35, v54, vcc
	v_mul_f32_e32 v8, v8, v35
	s_waitcnt vmcnt(3)
	v_mul_f32_e32 v8, v46, v8
	v_cvt_pk_bf16_f32 v8, v8, s0
	global_store_short v[40:41], v8, off
	v_mul_f32_e32 v8, v12, v35
	s_waitcnt vmcnt(2)
	v_mul_f32_e32 v8, v47, v8
	v_cvt_pk_bf16_f32 v8, v8, s0
	global_store_short v[42:43], v8, off
	v_mul_f32_e32 v8, v16, v35
	v_mul_f32_e32 v12, 0x4b800000, v34
	v_cmp_gt_f32_e32 vcc, s90, v34
	v_mul_f32_e32 v8, v48, v8
	v_cvt_pk_bf16_f32 v8, v8, s0
	v_cndmask_b32_e32 v12, v34, v12, vcc
	v_rsq_f32_e32 v12, v12
	global_store_short v[44:45], v8, off
	v_mul_f32_e32 v8, v20, v35
	v_lshlrev_b64 v[26:27], 1, v[26:27]
	s_waitcnt vmcnt(3)
	v_mul_f32_e32 v8, v49, v8
	v_lshl_add_u64 v[38:39], v[38:39], 0, v[26:27]
	v_cvt_pk_bf16_f32 v8, v8, s0
	global_store_short v[38:39], v8, off
	v_mul_f32_e32 v8, 0x45800000, v12
	v_cndmask_b32_e32 v20, v12, v8, vcc
	v_or_b32_e32 v34, 0x800, v32
	v_mov_b32_e32 v35, v33
	v_mul_f32_e32 v8, v9, v20
	v_lshl_add_u64 v[34:35], v[24:25], 0, v[34:35]
	v_mul_f32_e32 v8, v46, v8
	v_cvt_pk_bf16_f32 v12, v8, s0
	v_lshl_add_u64 v[8:9], v[34:35], 0, v[162:163]
	global_store_short v[8:9], v12, off
	v_mul_f32_e32 v8, v13, v20
	v_mul_f32_e32 v8, v47, v8
	v_cvt_pk_bf16_f32 v16, v8, s0
	v_mov_b32_e32 v8, v10
	v_mov_b32_e32 v9, v14
	v_mov_b32_e32 v38, v11
	v_mov_b32_e32 v39, v15
	v_pk_mul_f32 v[8:9], v[8:9], v[8:9]
	v_mov_b32_e32 v12, v18
	v_mov_b32_e32 v13, v22
	v_pk_mul_f32 v[38:39], v[38:39], v[38:39]
	v_mov_b32_e32 v40, v19
	v_mov_b32_e32 v41, v23
	v_pk_mul_f32 v[12:13], v[12:13], v[12:13]
	v_pk_mul_f32 v[40:41], v[40:41], v[40:41]
	v_mov_b32_e32 v42, v38
	v_mov_b32_e32 v43, v8
	v_mov_b32_e32 v8, v39
	v_pk_add_f32 v[8:9], v[42:43], v[8:9]
	v_mov_b32_e32 v38, v40
	v_mov_b32_e32 v39, v12
	v_pk_add_f32 v[8:9], v[8:9], v[38:39]
	v_mov_b32_e32 v12, v41
	v_pk_add_f32 v[8:9], v[8:9], v[12:13]
	ds_bpermute_b32 v13, v50, v9
	ds_bpermute_b32 v12, v50, v8
	v_lshl_add_u64 v[38:39], v[34:35], 0, v[28:29]
	global_store_short v[38:39], v16, off
	v_mul_f32_e32 v16, v17, v20
	v_mul_f32_e32 v16, v48, v16
	s_waitcnt lgkmcnt(0)
	v_pk_add_f32 v[8:9], v[8:9], v[12:13]
	ds_bpermute_b32 v13, v51, v9
	ds_bpermute_b32 v12, v51, v8
	v_cvt_pk_bf16_f32 v38, v16, s0
	v_lshl_add_u64 v[16:17], v[34:35], 0, v[30:31]
	global_store_short v[16:17], v38, off
	v_mul_f32_e32 v16, v21, v20
	s_waitcnt lgkmcnt(0)
	v_pk_add_f32 v[8:9], v[8:9], v[12:13]
	ds_bpermute_b32 v13, v52, v9
	ds_bpermute_b32 v12, v52, v8
	v_mul_f32_e32 v16, v49, v16
	v_cvt_pk_bf16_f32 v20, v16, s0
	v_lshl_add_u64 v[16:17], v[34:35], 0, v[26:27]
	global_store_short v[16:17], v20, off
	s_waitcnt lgkmcnt(0)
	v_pk_add_f32 v[8:9], v[8:9], v[12:13]
	ds_bpermute_b32 v13, v53, v9
	ds_bpermute_b32 v12, v53, v8
	v_or_b32_e32 v16, 0x1000, v32
	v_mov_b32_e32 v17, v33
	v_lshl_add_u64 v[16:17], v[24:25], 0, v[16:17]
	v_lshl_add_u64 v[20:21], v[16:17], 0, v[162:163]
	s_waitcnt lgkmcnt(0)
	v_pk_add_f32 v[8:9], v[8:9], v[12:13]
	v_lshl_add_u64 v[34:35], v[16:17], 0, v[30:31]
	v_pk_fma_f32 v[8:9], v[8:9], s[2:3], v[36:37] op_sel_hi:[1,0,0]
	v_or_b32_e32 v32, 0x1800, v32
	v_mul_f32_e32 v12, 0x4b800000, v9
	v_cmp_gt_f32_e32 vcc, s90, v9
	v_readlane_b32 s2, v253, 1
	v_readlane_b32 s3, v253, 2
	v_cndmask_b32_e32 v9, v9, v12, vcc
	v_rsq_f32_e32 v9, v9
	v_lshl_add_u64 v[12:13], v[16:17], 0, v[28:29]
	v_lshl_add_u64 v[16:17], v[16:17], 0, v[26:27]
	v_mul_f32_e32 v36, 0x45800000, v9
	v_cndmask_b32_e32 v9, v9, v36, vcc
	v_mul_f32_e32 v10, v10, v9
	v_mul_f32_e32 v10, v46, v10
	v_cvt_pk_bf16_f32 v10, v10, s0
	global_store_short v[20:21], v10, off
	v_mul_f32_e32 v10, v14, v9
	v_mul_f32_e32 v10, v47, v10
	v_cvt_pk_bf16_f32 v10, v10, s0
	global_store_short v[12:13], v10, off
	v_mul_f32_e32 v10, v18, v9
	v_mul_f32_e32 v10, v48, v10
	v_cvt_pk_bf16_f32 v10, v10, s0
	global_store_short v[34:35], v10, off
	v_mul_f32_e32 v10, 0x4b800000, v8
	v_cmp_gt_f32_e32 vcc, s90, v8
	v_mul_f32_e32 v9, v22, v9
	v_mul_f32_e32 v9, v49, v9
	v_cndmask_b32_e32 v8, v8, v10, vcc
	v_rsq_f32_e32 v8, v8
	v_cvt_pk_bf16_f32 v9, v9, s0
	global_store_short v[16:17], v9, off
	v_mul_f32_e32 v9, 0x45800000, v8
	v_cndmask_b32_e32 v12, v8, v9, vcc
	v_mul_f32_e32 v10, v11, v12
	v_lshl_add_u64 v[8:9], v[24:25], 0, v[32:33]
	v_mul_f32_e32 v10, v46, v10
	v_cvt_pk_bf16_f32 v13, v10, s0
	v_lshl_add_u64 v[10:11], v[8:9], 0, v[162:163]
	global_store_short v[10:11], v13, off
	v_mul_f32_e32 v10, v15, v12
	v_mul_f32_e32 v10, v47, v10
	v_cvt_pk_bf16_f32 v13, v10, s0
	v_lshl_add_u64 v[10:11], v[8:9], 0, v[28:29]
	global_store_short v[10:11], v13, off
	v_mul_f32_e32 v10, v19, v12
	v_mul_f32_e32 v10, v48, v10
	v_cvt_pk_bf16_f32 v13, v10, s0
	v_lshl_add_u64 v[10:11], v[8:9], 0, v[30:31]
	global_store_short v[10:11], v13, off
	v_mul_f32_e32 v10, v23, v12
	v_mul_f32_e32 v10, v49, v10
	v_cvt_pk_bf16_f32 v10, v10, s0
	v_lshl_add_u64 v[8:9], v[8:9], 0, v[26:27]
	global_store_short v[8:9], v10, off
	s_load_dword s2, s[2:3], 0x0
	s_waitcnt lgkmcnt(0)
	s_add_i32 s2, s95, s2
	s_add_i32 s95, s2, -16
	s_cmpk_lt_i32 s95, 0x408
	s_cbranch_scc0 .LBB0_1109

.LBB0_1370:
	s_or_b64 exec, exec, s[2:3]
	v_readlane_b32 s2, v253, 1
	v_readlane_b32 s3, v253, 2
	s_load_dword s3, s[2:3], 0x0
	s_waitcnt vmcnt(1)
	v_mov_b64_e32 v[56:57], v[64:65]
	s_waitcnt vmcnt(0)
	v_mov_b64_e32 v[60:61], v[68:69]
	v_mov_b64_e32 v[58:59], v[66:67]
	v_mov_b64_e32 v[62:63], v[70:71]
	s_waitcnt lgkmcnt(0)
	s_add_i32 s2, s3, s95
	s_cmpk_gt_i32 s2, 0xc27
	s_cbranch_scc1 .LBB0_1372
	v_lshl_add_u32 v56, s3, 3, v86
	v_subrev_u32_e32 v60, 128, v56
	v_ashrrev_i32_e32 v56, 5, v60
	s_mov_b32 s3, 0xfe03f81
	v_mul_hi_i32 v57, v56, s3
	v_lshrrev_b32_e32 v58, 31, v57
	v_ashrrev_i32_e32 v57, 4, v57
	v_add_u32_e32 v57, v57, v58
	v_mul_i32_i24_e32 v58, 0x102, v57
	v_sub_u32_e32 v56, v56, v58
	v_mul_hi_i32_i24_e32 v59, 0x4080, v57
	v_mul_i32_i24_e32 v58, 0x4080, v57
	v_ashrrev_i32_e32 v57, 31, v56
	v_lshlrev_b64 v[56:57], 6, v[56:57]
	v_mov_b32_e32 v61, v160
	v_lshl_add_u64 v[56:57], v[58:59], 0, v[56:57]
	s_nop 0
	v_and_or_b32 v56, v61, 63, v56
	v_mad_u64_u32 v[58:59], s[4:5], v56, s97, v[82:83]
	v_mov_b32_e32 v56, v59
	v_mad_u64_u32 v[56:57], s[4:5], v57, s97, v[56:57]
	v_mov_b32_e32 v59, v56
	v_lshlrev_b32_e32 v56, 5, v60
	v_and_b32_e32 v162, 0x3e0, v56
	v_lshl_add_u64 v[60:61], v[58:59], 0, v[162:163]
	global_load_dwordx4 v[56:59], v[60:61], off offset:3600
	s_nop 0
	global_load_dwordx4 v[60:63], v[60:61], off offset:3584

.LBB0_1373:
	v_add_u32_e32 v64, s4, v92
	ds_read_b128 v[64:67], v64
	v_add_u32_e32 v95, 0x1000, v86
	v_add_u32_e32 v97, 0x1800, v86
	s_mov_b32 s3, 0x8100000
	s_waitcnt lgkmcnt(0)
	v_mfma_f32_16x16x32_bf16 v[98:101], v[28:31], v[64:67], 0
	v_mfma_f32_16x16x32_bf16 v[102:105], v[24:27], v[64:67], 0
	s_nop 6
	v_cvt_pk_bf16_f32 v106, v98, v99
	v_cvt_pk_bf16_f32 v107, v100, v101
	v_mfma_f32_16x16x32_bf16 v[98:101], v[20:23], v[64:67], 0
	v_cvt_pk_bf16_f32 v108, v102, v103
	v_cvt_pk_bf16_f32 v109, v104, v105
	v_mfma_f32_16x16x32_bf16 v[102:105], v[16:19], v[64:67], 0
	s_nop 4
	v_cvt_pk_bf16_f32 v98, v98, v99
	v_cvt_pk_bf16_f32 v99, v100, v101
	ds_write2_b64 v95, v[106:107], v[98:99] offset1:4
	v_cvt_pk_bf16_f32 v100, v102, v103
	v_cvt_pk_bf16_f32 v101, v104, v105
	ds_write2_b64 v97, v[108:109], v[100:101] offset0:32 offset1:36
	v_mfma_f32_16x16x32_bf16 v[98:101], v[12:15], v[64:67], 0
	v_mfma_f32_16x16x32_bf16 v[102:105], v[8:11], v[64:67], 0
	s_nop 6
	v_cvt_pk_bf16_f32 v106, v98, v99
	v_cvt_pk_bf16_f32 v107, v100, v101
	v_mfma_f32_16x16x32_bf16 v[98:101], v[48:51], v[64:67], 0
	v_cvt_pk_bf16_f32 v102, v102, v103
	v_cvt_pk_bf16_f32 v103, v104, v105
	v_mfma_f32_16x16x32_bf16 v[64:67], v[52:55], v[64:67], 0
	s_nop 4
	v_cvt_pk_bf16_f32 v98, v98, v99
	v_cvt_pk_bf16_f32 v99, v100, v101
	s_nop 0
	v_cvt_pk_bf16_f32 v64, v64, v65
	v_cvt_pk_bf16_f32 v65, v66, v67
	ds_write2_b64 v95, v[106:107], v[98:99] offset0:8 offset1:12
	ds_write2_b64 v97, v[102:103], v[64:65] offset0:40 offset1:44
	s_waitcnt lgkmcnt(0)
	ds_read_u16 v64, v87 offset:4096
	s_waitcnt lgkmcnt(0)
	v_lshlrev_b32_e32 v66, 16, v64
	ds_read_u16 v64, v87 offset:6400
	s_waitcnt lgkmcnt(0)
	v_lshlrev_b32_e32 v95, 16, v64
	v_pk_mul_f32 v[64:65], v[76:77], v[70:71]
	s_nop 0
	v_sub_f32_e32 v64, v64, v65
	v_add_f32_e32 v64, v64, v66
	v_pk_mul_f32 v[66:67], v[84:85], v[70:71]
	s_nop 0
	v_add_f32_e32 v65, v66, v67
	v_add_f32_e32 v66, v65, v95
	v_cvt_pk_bf16_f32 v65, v64, s0
	ds_write_b16 v87, v65 offset:8704
	v_cvt_pk_bf16_f32 v65, v66, s0
	ds_write_b16 v87, v65 offset:8832
	ds_read_u16 v65, v87 offset:4384
	s_waitcnt lgkmcnt(0)
	v_lshlrev_b32_e32 v95, 16, v65
	ds_read_u16 v65, v87 offset:6688
	s_waitcnt lgkmcnt(0)
	v_lshlrev_b32_e32 v97, 16, v65
	ds_read_u16 v65, v87 offset:4240
	ds_read_u16 v67, v87 offset:6544
	s_waitcnt lgkmcnt(1)
	v_lshlrev_b32_e32 v70, 16, v65
	s_waitcnt lgkmcnt(0)
	v_lshlrev_b32_e32 v71, 16, v67
	v_pk_mul_f32 v[66:67], v[84:85], v[66:67] op_sel_hi:[1,0]
	s_nop 0
	v_pk_fma_f32 v[98:99], v[76:77], v[64:65], v[66:67] neg_lo:[0,0,1] neg_hi:[0,0,1]
	v_pk_fma_f32 v[64:65], v[76:77], v[64:65], v[66:67] op_sel_hi:[1,0,1]
	s_nop 0
	v_mov_b32_e32 v99, v65
	v_pk_add_f32 v[64:65], v[98:99], v[70:71]
	s_nop 0
	v_cvt_pk_bf16_f32 v66, v64, s0
	ds_write_b16 v87, v66 offset:8976
	v_cvt_pk_bf16_f32 v66, v65, s0
	ds_write_b16 v87, v66 offset:9104
	v_pk_mul_f32 v[66:67], v[76:77], v[64:65]
	v_pk_mul_f32 v[64:65], v[84:85], v[64:65]
	v_sub_f32_e32 v66, v66, v67
	v_add_f32_e32 v66, v66, v95
	v_add_f32_e32 v64, v64, v65
	v_add_f32_e32 v64, v64, v97
	v_cvt_pk_bf16_f32 v65, v66, s0
	ds_write_b16 v87, v65 offset:9248
	v_cvt_pk_bf16_f32 v65, v64, s0
	ds_write_b16 v87, v65 offset:9376
	ds_read_u16 v65, v87 offset:4672
	s_waitcnt lgkmcnt(0)
	v_lshlrev_b32_e32 v95, 16, v65
	ds_read_u16 v65, v87 offset:6976
	s_waitcnt lgkmcnt(0)
	v_lshlrev_b32_e32 v97, 16, v65
	ds_read_u16 v65, v87 offset:4528
	ds_read_u16 v67, v87 offset:6832
	s_waitcnt lgkmcnt(1)
	v_lshlrev_b32_e32 v70, 16, v65
	v_pk_mul_f32 v[64:65], v[84:85], v[64:65] op_sel_hi:[1,0]
	s_waitcnt lgkmcnt(0)
	v_lshlrev_b32_e32 v71, 16, v67
	v_pk_fma_f32 v[98:99], v[76:77], v[66:67], v[64:65] neg_lo:[0,0,1] neg_hi:[0,0,1]
	v_pk_fma_f32 v[64:65], v[76:77], v[66:67], v[64:65] op_sel_hi:[1,0,1]
	s_nop 0
	v_mov_b32_e32 v99, v65
	v_pk_add_f32 v[64:65], v[98:99], v[70:71]
	s_nop 0
	v_cvt_pk_bf16_f32 v66, v64, s0
	ds_write_b16 v87, v66 offset:9520
	v_cvt_pk_bf16_f32 v66, v65, s0
	ds_write_b16 v87, v66 offset:9648
	v_pk_mul_f32 v[66:67], v[76:77], v[64:65]
	v_pk_mul_f32 v[64:65], v[84:85], v[64:65]
	v_sub_f32_e32 v66, v66, v67
	v_add_f32_e32 v66, v66, v95
	v_add_f32_e32 v64, v64, v65
	v_add_f32_e32 v64, v64, v97
	v_cvt_pk_bf16_f32 v65, v66, s0
	ds_write_b16 v87, v65 offset:9792
	v_cvt_pk_bf16_f32 v65, v64, s0
	ds_write_b16 v87, v65 offset:9920
	ds_read_u16 v65, v87 offset:4960
	s_waitcnt lgkmcnt(0)
	v_lshlrev_b32_e32 v95, 16, v65
	ds_read_u16 v65, v87 offset:7264
	s_waitcnt lgkmcnt(0)
	v_lshlrev_b32_e32 v97, 16, v65
	ds_read_u16 v65, v87 offset:4816
	ds_read_u16 v67, v87 offset:7120
	s_waitcnt lgkmcnt(1)
	v_lshlrev_b32_e32 v70, 16, v65
	v_pk_mul_f32 v[64:65], v[84:85], v[64:65] op_sel_hi:[1,0]
	s_waitcnt lgkmcnt(0)
	v_lshlrev_b32_e32 v71, 16, v67
	v_pk_fma_f32 v[98:99], v[76:77], v[66:67], v[64:65] neg_lo:[0,0,1] neg_hi:[0,0,1]
	v_pk_fma_f32 v[64:65], v[76:77], v[66:67], v[64:65] op_sel_hi:[1,0,1]
	s_nop 0
	v_mov_b32_e32 v99, v65
	v_pk_add_f32 v[64:65], v[98:99], v[70:71]
	s_nop 0
	v_cvt_pk_bf16_f32 v66, v64, s0
	ds_write_b16 v87, v66 offset:10064
	v_cvt_pk_bf16_f32 v66, v65, s0
	ds_write_b16 v87, v66 offset:10192
	v_pk_mul_f32 v[66:67], v[76:77], v[64:65]
	v_pk_mul_f32 v[64:65], v[84:85], v[64:65]
	v_sub_f32_e32 v66, v66, v67
	v_add_f32_e32 v66, v66, v95
	v_add_f32_e32 v64, v64, v65
	v_add_f32_e32 v64, v64, v97
	v_cvt_pk_bf16_f32 v65, v66, s0
	ds_write_b16 v87, v65 offset:10336
	v_cvt_pk_bf16_f32 v65, v64, s0
	ds_write_b16 v87, v65 offset:10464
	ds_read_u16 v65, v87 offset:5248
	s_waitcnt lgkmcnt(0)
	v_lshlrev_b32_e32 v95, 16, v65
	ds_read_u16 v65, v87 offset:7552
	s_waitcnt lgkmcnt(0)
	v_lshlrev_b32_e32 v97, 16, v65
	ds_read_u16 v65, v87 offset:5104
	ds_read_u16 v67, v87 offset:7408
	s_waitcnt lgkmcnt(1)
	v_lshlrev_b32_e32 v70, 16, v65
	v_pk_mul_f32 v[64:65], v[84:85], v[64:65] op_sel_hi:[1,0]
	s_waitcnt lgkmcnt(0)
	v_lshlrev_b32_e32 v71, 16, v67
	v_pk_fma_f32 v[98:99], v[76:77], v[66:67], v[64:65] neg_lo:[0,0,1] neg_hi:[0,0,1]
	v_pk_fma_f32 v[64:65], v[76:77], v[66:67], v[64:65] op_sel_hi:[1,0,1]
	s_nop 0
	v_mov_b32_e32 v99, v65
	v_pk_add_f32 v[64:65], v[98:99], v[70:71]
	s_nop 0
	v_cvt_pk_bf16_f32 v66, v64, s0
	ds_write_b16 v87, v66 offset:10608
	v_cvt_pk_bf16_f32 v66, v65, s0
	ds_write_b16 v87, v66 offset:10736
	v_pk_mul_f32 v[66:67], v[76:77], v[64:65]
	v_pk_mul_f32 v[64:65], v[84:85], v[64:65]
	v_sub_f32_e32 v66, v66, v67
	v_add_f32_e32 v66, v66, v95
	v_add_f32_e32 v64, v64, v65
	v_add_f32_e32 v64, v64, v97
	v_cvt_pk_bf16_f32 v65, v66, s0
	ds_write_b16 v87, v65 offset:10880
	v_cvt_pk_bf16_f32 v65, v64, s0
	ds_write_b16 v87, v65 offset:11008
	ds_read_u16 v65, v87 offset:5536
	s_waitcnt lgkmcnt(0)
	v_lshlrev_b32_e32 v95, 16, v65
	ds_read_u16 v65, v87 offset:7840
	s_waitcnt lgkmcnt(0)
	v_lshlrev_b32_e32 v97, 16, v65
	ds_read_u16 v65, v87 offset:5392
	ds_read_u16 v67, v87 offset:7696
	s_waitcnt lgkmcnt(1)
	v_lshlrev_b32_e32 v70, 16, v65
	v_pk_mul_f32 v[64:65], v[84:85], v[64:65] op_sel_hi:[1,0]
	s_waitcnt lgkmcnt(0)
	v_lshlrev_b32_e32 v71, 16, v67
	v_pk_fma_f32 v[98:99], v[76:77], v[66:67], v[64:65] neg_lo:[0,0,1] neg_hi:[0,0,1]
	v_pk_fma_f32 v[64:65], v[76:77], v[66:67], v[64:65] op_sel_hi:[1,0,1]
	s_nop 0
	v_mov_b32_e32 v99, v65
	v_pk_add_f32 v[64:65], v[98:99], v[70:71]
	s_nop 0
	v_cvt_pk_bf16_f32 v66, v64, s0
	ds_write_b16 v87, v66 offset:11152
	v_cvt_pk_bf16_f32 v66, v65, s0
	ds_write_b16 v87, v66 offset:11280
	v_pk_mul_f32 v[66:67], v[76:77], v[64:65]
	v_pk_mul_f32 v[64:65], v[84:85], v[64:65]
	v_sub_f32_e32 v66, v66, v67
	v_add_f32_e32 v66, v66, v95
	v_add_f32_e32 v64, v64, v65
	v_add_f32_e32 v64, v64, v97
	v_cvt_pk_bf16_f32 v65, v66, s0
	ds_write_b16 v87, v65 offset:11424
	v_cvt_pk_bf16_f32 v65, v64, s0
	ds_write_b16 v87, v65 offset:11552
	ds_read_u16 v65, v87 offset:5824
	s_waitcnt lgkmcnt(0)
	v_lshlrev_b32_e32 v95, 16, v65
	ds_read_u16 v65, v87 offset:8128
	s_waitcnt lgkmcnt(0)
	v_lshlrev_b32_e32 v97, 16, v65
	ds_read_u16 v65, v87 offset:5680
	ds_read_u16 v67, v87 offset:7984
	s_waitcnt lgkmcnt(1)
	v_lshlrev_b32_e32 v70, 16, v65
	v_pk_mul_f32 v[64:65], v[84:85], v[64:65] op_sel_hi:[1,0]
	s_waitcnt lgkmcnt(0)
	v_lshlrev_b32_e32 v71, 16, v67
	v_pk_fma_f32 v[98:99], v[76:77], v[66:67], v[64:65] neg_lo:[0,0,1] neg_hi:[0,0,1]
	v_pk_fma_f32 v[64:65], v[76:77], v[66:67], v[64:65] op_sel_hi:[1,0,1]
	s_nop 0
	v_mov_b32_e32 v99, v65
	v_pk_add_f32 v[64:65], v[98:99], v[70:71]
	s_nop 0
	v_cvt_pk_bf16_f32 v66, v64, s0
	ds_write_b16 v87, v66 offset:11696
	v_cvt_pk_bf16_f32 v66, v65, s0
	ds_write_b16 v87, v66 offset:11824
	v_pk_mul_f32 v[66:67], v[76:77], v[64:65]
	v_pk_mul_f32 v[64:65], v[84:85], v[64:65]
	v_sub_f32_e32 v66, v66, v67
	v_add_f32_e32 v66, v66, v95
	v_add_f32_e32 v64, v64, v65
	v_add_f32_e32 v64, v64, v97
	v_cvt_pk_bf16_f32 v65, v66, s0
	ds_write_b16 v87, v65 offset:11968
	v_cvt_pk_bf16_f32 v65, v64, s0
	ds_write_b16 v87, v65 offset:12096
	ds_read_u16 v65, v87 offset:6112
	s_waitcnt lgkmcnt(0)
	v_lshlrev_b32_e32 v95, 16, v65
	ds_read_u16 v65, v87 offset:8416
	s_waitcnt lgkmcnt(0)
	v_lshlrev_b32_e32 v97, 16, v65
	ds_read_u16 v65, v87 offset:5968
	ds_read_u16 v67, v87 offset:8272
	s_waitcnt lgkmcnt(1)
	v_lshlrev_b32_e32 v70, 16, v65
	v_pk_mul_f32 v[64:65], v[84:85], v[64:65] op_sel_hi:[1,0]
	s_waitcnt lgkmcnt(0)
	v_lshlrev_b32_e32 v71, 16, v67
	v_pk_fma_f32 v[98:99], v[76:77], v[66:67], v[64:65] neg_lo:[0,0,1] neg_hi:[0,0,1]
	v_pk_fma_f32 v[64:65], v[76:77], v[66:67], v[64:65] op_sel_hi:[1,0,1]
	s_nop 0
	v_mov_b32_e32 v99, v65
	v_pk_add_f32 v[64:65], v[98:99], v[70:71]
	s_nop 0
	v_cvt_pk_bf16_f32 v66, v64, s0
	ds_write_b16 v87, v66 offset:12240
	v_cvt_pk_bf16_f32 v66, v65, s0
	ds_write_b16 v87, v66 offset:12368
	v_pk_mul_f32 v[66:67], v[76:77], v[64:65]
	v_pk_mul_f32 v[64:65], v[84:85], v[64:65]
	v_sub_f32_e32 v66, v66, v67
	v_add_f32_e32 v66, v66, v95
	v_add_f32_e32 v64, v64, v65
	v_add_f32_e32 v64, v64, v97
	v_cvt_pk_bf16_f32 v65, v66, s0
	ds_write_b16 v87, v65 offset:12512
	v_cvt_pk_bf16_f32 v65, v64, s0
	ds_write_b16 v87, v65 offset:12640
	ds_read_u16 v65, v87 offset:6256
	ds_read_u16 v67, v87 offset:8560
	v_add_u32_e32 v95, s4, v93
	s_addk_i32 s4, 0x400
	s_waitcnt lgkmcnt(1)
	v_lshlrev_b32_e32 v70, 16, v65
	v_pk_mul_f32 v[64:65], v[84:85], v[64:65] op_sel_hi:[1,0]
	s_waitcnt lgkmcnt(0)
	v_lshlrev_b32_e32 v71, 16, v67
	v_pk_fma_f32 v[98:99], v[76:77], v[66:67], v[64:65] neg_lo:[0,0,1] neg_hi:[0,0,1]
	v_pk_fma_f32 v[64:65], v[76:77], v[66:67], v[64:65] op_sel_hi:[1,0,1]
	s_nop 0
	v_mov_b32_e32 v99, v65
	v_pk_add_f32 v[70:71], v[98:99], v[70:71]
	s_nop 0
	v_cvt_pk_bf16_f32 v64, v70, s0
	ds_write_b16 v87, v64 offset:12784
	v_cvt_pk_bf16_f32 v64, v71, s0
	ds_write_b16 v87, v64 offset:12912
	s_waitcnt lgkmcnt(0)
	ds_read_b128 v[64:67], v94 offset:8704
	ds_read_b128 v[98:101], v94 offset:8768
	s_waitcnt lgkmcnt(1)
	v_mfma_f32_16x16x32_bf16 v[64:67], v[64:67], v[32:35], 0
	ds_read_u16 v97, v95
	s_waitcnt lgkmcnt(0)
	v_lshlrev_b32_e32 v97, 16, v97
	v_mfma_f32_16x16x32_bf16 v[64:67], v[98:101], v[36:39], v[64:67]
	ds_read_b128 v[98:101], v94 offset:8832
	s_waitcnt lgkmcnt(0)
	v_mfma_f32_16x16x32_bf16 v[64:67], v[98:101], v[40:43], v[64:67]
	ds_read_b128 v[98:101], v94 offset:8896
	s_waitcnt lgkmcnt(0)
	v_mfma_f32_16x16x32_bf16 v[64:67], v[98:101], v[44:47], v[64:67]
	v_lshl_add_u64 v[98:99], v[68:69], 0, s[6:7]
	v_add_co_u32_e32 v98, vcc, s3, v98
	s_nop 5
	v_fma_f32 v64, v91, v97, v64
	v_mul_f32_e32 v97, 0x3d372713, v64
	v_mul_f32_e32 v97, v64, v97
	v_fma_f32 v97, v64, v97, v64
	v_mul_f32_e32 v97, 0x3f4c422a, v97
	v_add_f32_e32 v97, v97, v97
	v_mul_f32_e32 v97, 0x3fb8aa3b, v97
	v_exp_f32_e32 v97, v97
	v_mul_f32_e32 v64, 0.5, v64
	v_addc_co_u32_e32 v99, vcc, 0, v99, vcc
	v_add_f32_e32 v97, 1.0, v97
	v_rcp_f32_e32 v97, v97
	s_add_u32 s6, s6, 0x4000
	s_addc_u32 s7, s7, 0
	s_cmpk_lg_i32 s4, 0x1000
	v_fma_f32 v97, v97, -2.0, 1.0
	v_add_f32_e32 v97, 1.0, v97
	v_mul_f32_e32 v64, v64, v97
	v_cvt_pk_bf16_f32 v64, v64, s0
	global_store_short v[98:99], v64, off
	ds_read_u16 v64, v95 offset:64
	s_waitcnt lgkmcnt(0)
	v_lshlrev_b32_e32 v64, 16, v64
	v_fma_f32 v64, v91, v64, v65
	v_mul_f32_e32 v65, 0x3d372713, v64
	v_mul_f32_e32 v65, v64, v65
	v_fma_f32 v65, v64, v65, v64
	v_mul_f32_e32 v65, 0x3f4c422a, v65
	v_add_f32_e32 v65, v65, v65
	v_mul_f32_e32 v65, 0x3fb8aa3b, v65
	v_exp_f32_e32 v65, v65
	v_mul_f32_e32 v64, 0.5, v64
	v_add_f32_e32 v65, 1.0, v65
	v_rcp_f32_e32 v65, v65
	s_nop 0
	v_fma_f32 v65, v65, -2.0, 1.0
	v_add_f32_e32 v65, 1.0, v65
	v_mul_f32_e32 v64, v64, v65
	v_cvt_pk_bf16_f32 v64, v64, s0
	global_store_short v[98:99], v64, off offset:1024
	ds_read_u16 v64, v95 offset:128
	s_waitcnt lgkmcnt(0)
	v_lshlrev_b32_e32 v64, 16, v64
	v_fma_f32 v64, v91, v64, v66
	v_mul_f32_e32 v65, 0x3d372713, v64
	v_mul_f32_e32 v65, v64, v65
	v_fma_f32 v65, v64, v65, v64
	v_mul_f32_e32 v65, 0x3f4c422a, v65
	v_add_f32_e32 v65, v65, v65
	v_mul_f32_e32 v65, 0x3fb8aa3b, v65
	v_exp_f32_e32 v65, v65
	v_mul_f32_e32 v64, 0.5, v64
	v_add_f32_e32 v65, 1.0, v65
	v_rcp_f32_e32 v65, v65
	s_nop 0
	v_fma_f32 v65, v65, -2.0, 1.0
	v_add_f32_e32 v65, 1.0, v65
	v_mul_f32_e32 v64, v64, v65
	v_cvt_pk_bf16_f32 v64, v64, s0
	global_store_short v[98:99], v64, off offset:2048
	ds_read_u16 v64, v95 offset:192
	s_waitcnt lgkmcnt(0)
	v_lshlrev_b32_e32 v64, 16, v64
	v_fmac_f32_e32 v67, v91, v64
	v_mul_f32_e32 v64, 0x3d372713, v67
	v_mul_f32_e32 v64, v67, v64
	v_fma_f32 v64, v67, v64, v67
	v_mul_f32_e32 v64, 0x3f4c422a, v64
	v_add_f32_e32 v64, v64, v64
	v_mul_f32_e32 v64, 0x3fb8aa3b, v64
	v_exp_f32_e32 v64, v64
	v_mul_f32_e32 v65, 0.5, v67
	v_add_f32_e32 v64, 1.0, v64
	v_rcp_f32_e32 v64, v64
	s_nop 0
	v_fma_f32 v64, v64, -2.0, 1.0
	v_add_f32_e32 v64, 1.0, v64
	v_mul_f32_e32 v64, v65, v64
	v_cvt_pk_bf16_f32 v64, v64, s0
	global_store_short v[98:99], v64, off offset:3072
	s_waitcnt lgkmcnt(0)
	s_cbranch_scc1 .LBB0_1373
	s_add_i32 s95, s2, -16
	v_mov_b64_e32 v[70:71], v[62:63]
	v_mov_b64_e32 v[66:67], v[58:59]
	s_cmpk_lt_i32 s95, 0xc18
	v_mov_b64_e32 v[68:69], v[60:61]
	v_mov_b64_e32 v[64:65], v[56:57]
	s_barrier
	s_cbranch_scc1 .LBB0_1240

.LBB0_1376:
	s_and_b64 vcc, exec, s[2:3]
	s_cbranch_vccz .LBB0_1387
	v_readlane_b32 s6, v253, 0
	s_waitcnt vmcnt(0) lgkmcnt(0)
	v_mov_b32_e32 v2, v160
	s_movk_i32 s2, 0x101
	s_lshr_b32 s4, s6, 1
	s_mul_i32 s4, s4, 0x102
	v_cmp_lt_i32_e32 vcc, s2, v2
	s_and_saveexec_b64 s[2:3], vcc
	s_xor_b64 s[2:3], exec, s[2:3]
	s_or_saveexec_b64 s[2:3], s[2:3]
	v_mov_b32_e32 v50, s4
	s_xor_b64 exec, exec, s[2:3]
	s_cbranch_execz .LBB0_1379
	v_add_u32_e32 v4, s4, v2
	v_ashrrev_i32_e32 v5, 31, v4
	v_lshl_add_u64 v[4:5], v[4:5], 2, v[0:1]
	v_add_co_u32_e32 v4, vcc, 0x50a0000, v4
	v_lshl_add_u32 v3, v2, 2, v195
	s_nop 0
	v_addc_co_u32_e32 v5, vcc, 0, v5, vcc
	global_load_dword v4, v[4:5], off
	v_add_u32_e32 v3, 0x15800, v3
	v_mov_b32_e32 v50, s4
	s_waitcnt vmcnt(0)
	ds_write_b32 v3, v4
.LBB0_1379:
	s_or_b64 exec, exec, s[2:3]
	v_readfirstlane_b32 s10, v0
	v_readfirstlane_b32 s11, v1
	v_readfirstlane_b32 s8, v2
	s_nop 3
	s_lshr_b32 s8, s8, 6
	s_and_b32 s5, s6, 1
	s_lshr_b32 s7, s6, 1
	s_mul_i32 s9, s4, 0x2000
	s_add_u32 s12, s10, s9
	s_addc_u32 s13, s11, 0
	s_add_u32 s14, s12, 0x1020000
	s_addc_u32 s15, s13, 0
	s_add_u32 s16, s12, 0x2040000
	s_addc_u32 s17, s13, 0
	s_add_u32 s18, s12, 0x3060000
	s_addc_u32 s19, s13, 0
	s_cmp_lt_u32 s8, 4
	s_cbranch_scc0 .Ldn_loader
	s_cmp_lt_u32 s8, 2
	s_cbranch_scc0 .Ldn_idle
	s_lshl_b32 s3, s5, 1
	s_add_u32 s3, s3, s8
	v_and_b32_e32 v3, 63, v2
	v_and_b32_e32 v4, 15, v2
	v_bfe_u32 v5, v2, 4, 2
	v_mul_u32_u24_e32 v6, 0x90, v4
	v_lshl_add_u32 v6, v5, 3, v6
	v_add_u32_e32 v42, v195, v6
	v_lshlrev_b32_e32 v6, 5, v3
	s_lshl_b32 s9, s3, 11
	v_add3_u32 v43, v195, v6, s9
	v_add_u32_e32 v44, 0x15800, v195
	v_lshlrev_b32_e32 v6, 12, v5
	v_and_b32_e32 v7, 3, v4
	v_lshl_add_u32 v6, v7, 10, v6
	v_lshrrev_b32_e32 v7, 2, v4
	v_lshl_add_u32 v45, v7, 4, v6
	v_and_b32_e32 v6, 1, v2
	v_cmp_eq_u32_e64 s[24:25], 1, v6
	v_and_b32_e32 v6, 2, v2
	v_cmp_eq_u32_e64 s[28:29], 2, v6
	s_nop 3
	s_not_b64 s[26:27], s[24:25]
	s_not_b64 s[30:31], s[28:29]
	v_add_u32_e32 v46, 0x4000, v45
	v_add_u32_e32 v47, 0x8000, v45
	v_add_u32_e32 v48, 0xc000, v45
	s_lshr_b32 s22, s7, 2
	s_mul_i32 s22, s22, 0x1020000
	s_and_b32 s23, s7, 3
	s_lshl_b32 s23, s23, 8
	s_add_u32 s22, s22, s23
	s_lshl_b32 s23, s3, 6
	s_add_u32 s22, s22, s23
	s_add_u32 s22, s22, 0x50a2100
	s_add_u32 s20, s10, s22
	s_addc_u32 s21, s11, 0
	v_mov_b32_e32 v50, 0
	v_mov_b32_e32 v51, 0
	v_mov_b32_e32 v52, 0
	v_mov_b32_e32 v53, 0
	v_mov_b32_e32 v54, 0
	v_mov_b32_e32 v55, 0
	v_mov_b32_e32 v56, 0
	v_mov_b32_e32 v57, 0
	v_mov_b32_e32 v58, 0
	v_mov_b32_e32 v59, 0
	v_mov_b32_e32 v60, 0
	v_mov_b32_e32 v61, 0
	v_mov_b32_e32 v62, 0
	v_mov_b32_e32 v63, 0
	v_mov_b32_e32 v64, 0
	v_mov_b32_e32 v65, 0
	v_mov_b32_e32 v66, 0
	v_mov_b32_e32 v67, 0
	v_mov_b32_e32 v68, 0
	v_mov_b32_e32 v69, 0
	v_mov_b32_e32 v70, 0
	v_mov_b32_e32 v71, 0
	v_mov_b32_e32 v72, 0
	v_mov_b32_e32 v73, 0
	s_mov_b32 s22, 0
	s_waitcnt lgkmcnt(0)
	s_barrier
.Ldn_c_loop:
	ds_read_b32 v154, v44 offset:0
	ds_read_b128 v[138:141], v43 offset:18432
	ds_read_b128 v[142:145], v43 offset:18448
	ds_read_b64 v[74:75], v42 offset:0
	ds_read_b64 v[76:77], v42 offset:32
	ds_read_b64 v[78:79], v42 offset:64
	ds_read_b64 v[80:81], v42 offset:96
	ds_read_b64 v[82:83], v42 offset:2304
	ds_read_b64 v[84:85], v42 offset:2336
	ds_read_b64 v[86:87], v42 offset:2368
	ds_read_b64 v[88:89], v42 offset:2400
	ds_read_b64 v[90:91], v42 offset:4608
	ds_read_b64 v[92:93], v42 offset:4640
	ds_read_b64 v[94:95], v42 offset:4672
	ds_read_b64 v[96:97], v42 offset:4704
	s_waitcnt lgkmcnt(12)
	v_lshlrev_b32_e32 v26, 16, v138
	v_and_b32_e32 v27, 0xffff0000, v138
	ds_read_b64 v[98:99], v42 offset:6912
	v_lshlrev_b32_e32 v28, 16, v139
	v_and_b32_e32 v29, 0xffff0000, v139
	ds_read_b64 v[100:101], v42 offset:6944
	v_lshlrev_b32_e32 v30, 16, v140
	v_and_b32_e32 v31, 0xffff0000, v140
	ds_read_b64 v[102:103], v42 offset:6976
	v_lshlrev_b32_e32 v32, 16, v141
	v_and_b32_e32 v33, 0xffff0000, v141
	ds_read_b64 v[104:105], v42 offset:7008
	v_lshlrev_b32_e32 v34, 16, v142
	v_and_b32_e32 v35, 0xffff0000, v142
	ds_read_b128 v[146:149], v43 offset:26624
	v_lshlrev_b32_e32 v36, 16, v143
	v_and_b32_e32 v37, 0xffff0000, v143
	ds_read_b128 v[150:153], v43 offset:26640
	v_lshlrev_b32_e32 v38, 16, v144
	v_and_b32_e32 v39, 0xffff0000, v144
	v_lshlrev_b32_e32 v40, 16, v145
	v_and_b32_e32 v41, 0xffff0000, v145
	v_fma_f32 v50, v50, v154, v26
	v_fma_f32 v51, v51, v154, v27
	v_fma_f32 v52, v52, v154, v28
	v_fma_f32 v53, v53, v154, v29
	v_fma_f32 v54, v54, v154, v30
	v_fma_f32 v55, v55, v154, v31
	v_fma_f32 v56, v56, v154, v32
	v_fma_f32 v57, v57, v154, v33
	v_fma_f32 v58, v58, v154, v34
	v_fma_f32 v59, v59, v154, v35
	v_fma_f32 v60, v60, v154, v36
	v_fma_f32 v61, v61, v154, v37
	v_fma_f32 v62, v62, v154, v38
	v_fma_f32 v63, v63, v154, v39
	v_fma_f32 v64, v64, v154, v40
	v_fma_f32 v65, v65, v154, v41
	s_waitcnt lgkmcnt(0)
	v_mfma_f32_16x16x32_bf16 v[50:53], v[74:77], v[66:69], v[50:53]
	ds_read_b64 v[106:107], v42 offset:9216
	ds_read_b64 v[108:109], v42 offset:9248
	v_lshlrev_b32_e32 v2, 16, v146
	v_and_b32_e32 v3, 0xffff0000, v146
	v_mfma_f32_16x16x32_bf16 v[54:57], v[82:85], v[66:69], v[54:57]
	ds_read_b64 v[110:111], v42 offset:9280
	ds_read_b64 v[112:113], v42 offset:9312
	v_lshlrev_b32_e32 v4, 16, v147
	v_and_b32_e32 v5, 0xffff0000, v147
	v_mfma_f32_16x16x32_bf16 v[58:61], v[90:93], v[66:69], v[58:61]
	ds_read_b64 v[114:115], v42 offset:11520
	ds_read_b64 v[116:117], v42 offset:11552
	v_lshlrev_b32_e32 v6, 16, v148
	v_and_b32_e32 v7, 0xffff0000, v148
	v_mfma_f32_16x16x32_bf16 v[62:65], v[98:101], v[66:69], v[62:65]
	ds_read_b64 v[118:119], v42 offset:11584
	ds_read_b64 v[120:121], v42 offset:11616
	v_lshlrev_b32_e32 v8, 16, v149
	v_and_b32_e32 v9, 0xffff0000, v149
	v_mfma_f32_16x16x32_bf16 v[50:53], v[78:81], v[70:73], v[50:53]
	ds_read_b64 v[122:123], v42 offset:13824
	ds_read_b64 v[124:125], v42 offset:13856
	v_lshlrev_b32_e32 v10, 16, v150
	v_and_b32_e32 v11, 0xffff0000, v150
	v_mfma_f32_16x16x32_bf16 v[54:57], v[86:89], v[70:73], v[54:57]
	ds_read_b64 v[126:127], v42 offset:13888
	ds_read_b64 v[128:129], v42 offset:13920
	v_lshlrev_b32_e32 v12, 16, v151
	v_and_b32_e32 v13, 0xffff0000, v151
	v_mfma_f32_16x16x32_bf16 v[58:61], v[94:97], v[70:73], v[58:61]
	ds_read_b64 v[130:131], v42 offset:16128
	ds_read_b64 v[132:133], v42 offset:16160
	v_lshlrev_b32_e32 v14, 16, v152
	v_and_b32_e32 v15, 0xffff0000, v152
	v_mfma_f32_16x16x32_bf16 v[62:65], v[102:105], v[70:73], v[62:65]
	ds_read_b64 v[134:135], v42 offset:16192
	ds_read_b64 v[136:137], v42 offset:16224
	v_lshlrev_b32_e32 v16, 16, v153
	v_and_b32_e32 v17, 0xffff0000, v153
	s_waitcnt lgkmcnt(12)
	v_mfma_f32_16x16x32_bf16 v[2:5], v[106:109], v[66:69], v[2:5]
	v_cvt_pk_bf16_f32 v18, v50, v51
	v_mfma_f32_16x16x32_bf16 v[2:5], v[110:113], v[70:73], v[2:5]
	v_cvt_pk_bf16_f32 v19, v52, v53
	s_waitcnt lgkmcnt(8)
	v_mfma_f32_16x16x32_bf16 v[6:9], v[114:117], v[66:69], v[6:9]
	v_cvt_pk_bf16_f32 v20, v54, v55
	v_mfma_f32_16x16x32_bf16 v[6:9], v[118:121], v[70:73], v[6:9]
	v_cvt_pk_bf16_f32 v21, v56, v57
	s_waitcnt lgkmcnt(4)
	v_mfma_f32_16x16x32_bf16 v[10:13], v[122:125], v[66:69], v[10:13]
	v_cvt_pk_bf16_f32 v22, v58, v59
	v_mfma_f32_16x16x32_bf16 v[10:13], v[126:129], v[70:73], v[10:13]
	v_cvt_pk_bf16_f32 v23, v60, v61
	s_waitcnt lgkmcnt(0)
	v_mfma_f32_16x16x32_bf16 v[14:17], v[130:133], v[66:69], v[14:17]
	v_cvt_pk_bf16_f32 v24, v62, v63
	v_mfma_f32_16x16x32_bf16 v[14:17], v[134:137], v[70:73], v[14:17]
	v_cvt_pk_bf16_f32 v25, v64, v65
	s_mov_b64 vcc, s[24:25]
	s_nop 1
	v_cndmask_b32_dpp v27, v2, v3, vcc quad_perm:[1,0,3,2] row_mask:0xf bank_mask:0xf
	v_cndmask_b32_dpp v29, v4, v5, vcc quad_perm:[1,0,3,2] row_mask:0xf bank_mask:0xf
	v_cndmask_b32_dpp v31, v6, v7, vcc quad_perm:[1,0,3,2] row_mask:0xf bank_mask:0xf
	v_cndmask_b32_dpp v33, v8, v9, vcc quad_perm:[1,0,3,2] row_mask:0xf bank_mask:0xf
	v_cndmask_b32_dpp v35, v10, v11, vcc quad_perm:[1,0,3,2] row_mask:0xf bank_mask:0xf
	v_cndmask_b32_dpp v37, v12, v13, vcc quad_perm:[1,0,3,2] row_mask:0xf bank_mask:0xf
	v_cndmask_b32_dpp v39, v14, v15, vcc quad_perm:[1,0,3,2] row_mask:0xf bank_mask:0xf
	v_cndmask_b32_dpp v41, v16, v17, vcc quad_perm:[1,0,3,2] row_mask:0xf bank_mask:0xf
	s_mov_b64 vcc, s[26:27]
	s_nop 1
	v_cndmask_b32_dpp v26, v3, v2, vcc quad_perm:[1,0,3,2] row_mask:0xf bank_mask:0xf
	v_cndmask_b32_dpp v28, v5, v4, vcc quad_perm:[1,0,3,2] row_mask:0xf bank_mask:0xf
	v_cndmask_b32_dpp v30, v7, v6, vcc quad_perm:[1,0,3,2] row_mask:0xf bank_mask:0xf
	v_cndmask_b32_dpp v32, v9, v8, vcc quad_perm:[1,0,3,2] row_mask:0xf bank_mask:0xf
	v_cndmask_b32_dpp v34, v11, v10, vcc quad_perm:[1,0,3,2] row_mask:0xf bank_mask:0xf
	v_cndmask_b32_dpp v36, v13, v12, vcc quad_perm:[1,0,3,2] row_mask:0xf bank_mask:0xf
	v_cndmask_b32_dpp v38, v15, v14, vcc quad_perm:[1,0,3,2] row_mask:0xf bank_mask:0xf
	v_cndmask_b32_dpp v40, v17, v16, vcc quad_perm:[1,0,3,2] row_mask:0xf bank_mask:0xf
	s_mov_b64 vcc, s[28:29]
	s_nop 1
	v_cndmask_b32_dpp v4, v26, v28, vcc quad_perm:[2,3,0,1] row_mask:0xf bank_mask:0xf
	v_cndmask_b32_dpp v5, v27, v29, vcc quad_perm:[2,3,0,1] row_mask:0xf bank_mask:0xf
	v_cndmask_b32_dpp v8, v30, v32, vcc quad_perm:[2,3,0,1] row_mask:0xf bank_mask:0xf
	v_cndmask_b32_dpp v9, v31, v33, vcc quad_perm:[2,3,0,1] row_mask:0xf bank_mask:0xf
	v_cndmask_b32_dpp v12, v34, v36, vcc quad_perm:[2,3,0,1] row_mask:0xf bank_mask:0xf
	v_cndmask_b32_dpp v13, v35, v37, vcc quad_perm:[2,3,0,1] row_mask:0xf bank_mask:0xf
	v_cndmask_b32_dpp v16, v38, v40, vcc quad_perm:[2,3,0,1] row_mask:0xf bank_mask:0xf
	v_cndmask_b32_dpp v17, v39, v41, vcc quad_perm:[2,3,0,1] row_mask:0xf bank_mask:0xf
	s_mov_b64 vcc, s[30:31]
	s_nop 1
	v_cndmask_b32_dpp v2, v28, v26, vcc quad_perm:[2,3,0,1] row_mask:0xf bank_mask:0xf
	v_cndmask_b32_dpp v3, v29, v27, vcc quad_perm:[2,3,0,1] row_mask:0xf bank_mask:0xf
	v_cndmask_b32_dpp v6, v32, v30, vcc quad_perm:[2,3,0,1] row_mask:0xf bank_mask:0xf
	v_cndmask_b32_dpp v7, v33, v31, vcc quad_perm:[2,3,0,1] row_mask:0xf bank_mask:0xf
	v_cndmask_b32_dpp v10, v36, v34, vcc quad_perm:[2,3,0,1] row_mask:0xf bank_mask:0xf
	v_cndmask_b32_dpp v11, v37, v35, vcc quad_perm:[2,3,0,1] row_mask:0xf bank_mask:0xf
	v_cndmask_b32_dpp v14, v40, v38, vcc quad_perm:[2,3,0,1] row_mask:0xf bank_mask:0xf
	v_cndmask_b32_dpp v15, v41, v39, vcc quad_perm:[2,3,0,1] row_mask:0xf bank_mask:0xf
	global_store_dwordx4 v45, v[2:5], s[20:21]
	global_store_dwordx4 v46, v[6:9], s[20:21]
	global_store_dwordx4 v47, v[10:13], s[20:21]
	global_store_dwordx4 v48, v[14:17], s[20:21]
	s_add_u32 s20, s20, 0x10000
	s_addc_u32 s21, s21, 0
	s_waitcnt lgkmcnt(0)
	s_barrier
	ds_read_b32 v154, v44 offset:4
	ds_read_b128 v[138:141], v43 offset:53248
	ds_read_b128 v[142:145], v43 offset:53264
	ds_read_b64 v[74:75], v42 offset:34816
	ds_read_b64 v[76:77], v42 offset:34848
	ds_read_b64 v[78:79], v42 offset:34880
	ds_read_b64 v[80:81], v42 offset:34912
	ds_read_b64 v[82:83], v42 offset:37120
	ds_read_b64 v[84:85], v42 offset:37152
	ds_read_b64 v[86:87], v42 offset:37184
	ds_read_b64 v[88:89], v42 offset:37216
	ds_read_b64 v[90:91], v42 offset:39424
	ds_read_b64 v[92:93], v42 offset:39456
	ds_read_b64 v[94:95], v42 offset:39488
	ds_read_b64 v[96:97], v42 offset:39520
	s_waitcnt lgkmcnt(12)
	v_lshlrev_b32_e32 v26, 16, v138
	v_and_b32_e32 v27, 0xffff0000, v138
	ds_read_b64 v[98:99], v42 offset:41728
	v_lshlrev_b32_e32 v28, 16, v139
	v_and_b32_e32 v29, 0xffff0000, v139
	ds_read_b64 v[100:101], v42 offset:41760
	v_lshlrev_b32_e32 v30, 16, v140
	v_and_b32_e32 v31, 0xffff0000, v140
	ds_read_b64 v[102:103], v42 offset:41792
	v_lshlrev_b32_e32 v32, 16, v141
	v_and_b32_e32 v33, 0xffff0000, v141
	ds_read_b64 v[104:105], v42 offset:41824
	v_lshlrev_b32_e32 v34, 16, v142
	v_and_b32_e32 v35, 0xffff0000, v142
	ds_read_b128 v[146:149], v43 offset:61440
	v_lshlrev_b32_e32 v36, 16, v143
	v_and_b32_e32 v37, 0xffff0000, v143
	ds_read_b128 v[150:153], v43 offset:61456
	v_lshlrev_b32_e32 v38, 16, v144
	v_and_b32_e32 v39, 0xffff0000, v144
	v_lshlrev_b32_e32 v40, 16, v145
	v_and_b32_e32 v41, 0xffff0000, v145
	v_fma_f32 v50, v50, v154, v26
	v_fma_f32 v51, v51, v154, v27
	v_fma_f32 v52, v52, v154, v28
	v_fma_f32 v53, v53, v154, v29
	v_fma_f32 v54, v54, v154, v30
	v_fma_f32 v55, v55, v154, v31
	v_fma_f32 v56, v56, v154, v32
	v_fma_f32 v57, v57, v154, v33
	v_fma_f32 v58, v58, v154, v34
	v_fma_f32 v59, v59, v154, v35
	v_fma_f32 v60, v60, v154, v36
	v_fma_f32 v61, v61, v154, v37
	v_fma_f32 v62, v62, v154, v38
	v_fma_f32 v63, v63, v154, v39
	v_fma_f32 v64, v64, v154, v40
	v_fma_f32 v65, v65, v154, v41
	s_waitcnt lgkmcnt(0)
	v_mfma_f32_16x16x32_bf16 v[50:53], v[74:77], v[18:21], v[50:53]
	ds_read_b64 v[106:107], v42 offset:44032
	ds_read_b64 v[108:109], v42 offset:44064
	v_lshlrev_b32_e32 v2, 16, v146
	v_and_b32_e32 v3, 0xffff0000, v146
	v_mfma_f32_16x16x32_bf16 v[54:57], v[82:85], v[18:21], v[54:57]
	ds_read_b64 v[110:111], v42 offset:44096
	ds_read_b64 v[112:113], v42 offset:44128
	v_lshlrev_b32_e32 v4, 16, v147
	v_and_b32_e32 v5, 0xffff0000, v147
	v_mfma_f32_16x16x32_bf16 v[58:61], v[90:93], v[18:21], v[58:61]
	ds_read_b64 v[114:115], v42 offset:46336
	ds_read_b64 v[116:117], v42 offset:46368
	v_lshlrev_b32_e32 v6, 16, v148
	v_and_b32_e32 v7, 0xffff0000, v148
	v_mfma_f32_16x16x32_bf16 v[62:65], v[98:101], v[18:21], v[62:65]
	ds_read_b64 v[118:119], v42 offset:46400
	ds_read_b64 v[120:121], v42 offset:46432
	v_lshlrev_b32_e32 v8, 16, v149
	v_and_b32_e32 v9, 0xffff0000, v149
	v_mfma_f32_16x16x32_bf16 v[50:53], v[78:81], v[22:25], v[50:53]
	ds_read_b64 v[122:123], v42 offset:48640
	ds_read_b64 v[124:125], v42 offset:48672
	v_lshlrev_b32_e32 v10, 16, v150
	v_and_b32_e32 v11, 0xffff0000, v150
	v_mfma_f32_16x16x32_bf16 v[54:57], v[86:89], v[22:25], v[54:57]
	ds_read_b64 v[126:127], v42 offset:48704
	ds_read_b64 v[128:129], v42 offset:48736
	v_lshlrev_b32_e32 v12, 16, v151
	v_and_b32_e32 v13, 0xffff0000, v151
	v_mfma_f32_16x16x32_bf16 v[58:61], v[94:97], v[22:25], v[58:61]
	ds_read_b64 v[130:131], v42 offset:50944
	ds_read_b64 v[132:133], v42 offset:50976
	v_lshlrev_b32_e32 v14, 16, v152
	v_and_b32_e32 v15, 0xffff0000, v152
	v_mfma_f32_16x16x32_bf16 v[62:65], v[102:105], v[22:25], v[62:65]
	ds_read_b64 v[134:135], v42 offset:51008
	ds_read_b64 v[136:137], v42 offset:51040
	v_lshlrev_b32_e32 v16, 16, v153
	v_and_b32_e32 v17, 0xffff0000, v153
	s_waitcnt lgkmcnt(12)
	v_mfma_f32_16x16x32_bf16 v[2:5], v[106:109], v[18:21], v[2:5]
	v_cvt_pk_bf16_f32 v66, v50, v51
	v_mfma_f32_16x16x32_bf16 v[2:5], v[110:113], v[22:25], v[2:5]
	v_cvt_pk_bf16_f32 v67, v52, v53
	s_waitcnt lgkmcnt(8)
	v_mfma_f32_16x16x32_bf16 v[6:9], v[114:117], v[18:21], v[6:9]
	v_cvt_pk_bf16_f32 v68, v54, v55
	v_mfma_f32_16x16x32_bf16 v[6:9], v[118:121], v[22:25], v[6:9]
	v_cvt_pk_bf16_f32 v69, v56, v57
	s_waitcnt lgkmcnt(4)
	v_mfma_f32_16x16x32_bf16 v[10:13], v[122:125], v[18:21], v[10:13]
	v_cvt_pk_bf16_f32 v70, v58, v59
	v_mfma_f32_16x16x32_bf16 v[10:13], v[126:129], v[22:25], v[10:13]
	v_cvt_pk_bf16_f32 v71, v60, v61
	s_waitcnt lgkmcnt(0)
	v_mfma_f32_16x16x32_bf16 v[14:17], v[130:133], v[18:21], v[14:17]
	v_cvt_pk_bf16_f32 v72, v62, v63
	v_mfma_f32_16x16x32_bf16 v[14:17], v[134:137], v[22:25], v[14:17]
	v_cvt_pk_bf16_f32 v73, v64, v65
	s_mov_b64 vcc, s[24:25]
	s_nop 1
	v_cndmask_b32_dpp v27, v2, v3, vcc quad_perm:[1,0,3,2] row_mask:0xf bank_mask:0xf
	v_cndmask_b32_dpp v29, v4, v5, vcc quad_perm:[1,0,3,2] row_mask:0xf bank_mask:0xf
	v_cndmask_b32_dpp v31, v6, v7, vcc quad_perm:[1,0,3,2] row_mask:0xf bank_mask:0xf
	v_cndmask_b32_dpp v33, v8, v9, vcc quad_perm:[1,0,3,2] row_mask:0xf bank_mask:0xf
	v_cndmask_b32_dpp v35, v10, v11, vcc quad_perm:[1,0,3,2] row_mask:0xf bank_mask:0xf
	v_cndmask_b32_dpp v37, v12, v13, vcc quad_perm:[1,0,3,2] row_mask:0xf bank_mask:0xf
	v_cndmask_b32_dpp v39, v14, v15, vcc quad_perm:[1,0,3,2] row_mask:0xf bank_mask:0xf
	v_cndmask_b32_dpp v41, v16, v17, vcc quad_perm:[1,0,3,2] row_mask:0xf bank_mask:0xf
	s_mov_b64 vcc, s[26:27]
	s_nop 1
	v_cndmask_b32_dpp v26, v3, v2, vcc quad_perm:[1,0,3,2] row_mask:0xf bank_mask:0xf
	v_cndmask_b32_dpp v28, v5, v4, vcc quad_perm:[1,0,3,2] row_mask:0xf bank_mask:0xf
	v_cndmask_b32_dpp v30, v7, v6, vcc quad_perm:[1,0,3,2] row_mask:0xf bank_mask:0xf
	v_cndmask_b32_dpp v32, v9, v8, vcc quad_perm:[1,0,3,2] row_mask:0xf bank_mask:0xf
	v_cndmask_b32_dpp v34, v11, v10, vcc quad_perm:[1,0,3,2] row_mask:0xf bank_mask:0xf
	v_cndmask_b32_dpp v36, v13, v12, vcc quad_perm:[1,0,3,2] row_mask:0xf bank_mask:0xf
	v_cndmask_b32_dpp v38, v15, v14, vcc quad_perm:[1,0,3,2] row_mask:0xf bank_mask:0xf
	v_cndmask_b32_dpp v40, v17, v16, vcc quad_perm:[1,0,3,2] row_mask:0xf bank_mask:0xf
	s_mov_b64 vcc, s[28:29]
	s_nop 1
	v_cndmask_b32_dpp v4, v26, v28, vcc quad_perm:[2,3,0,1] row_mask:0xf bank_mask:0xf
	v_cndmask_b32_dpp v5, v27, v29, vcc quad_perm:[2,3,0,1] row_mask:0xf bank_mask:0xf
	v_cndmask_b32_dpp v8, v30, v32, vcc quad_perm:[2,3,0,1] row_mask:0xf bank_mask:0xf
	v_cndmask_b32_dpp v9, v31, v33, vcc quad_perm:[2,3,0,1] row_mask:0xf bank_mask:0xf
	v_cndmask_b32_dpp v12, v34, v36, vcc quad_perm:[2,3,0,1] row_mask:0xf bank_mask:0xf
	v_cndmask_b32_dpp v13, v35, v37, vcc quad_perm:[2,3,0,1] row_mask:0xf bank_mask:0xf
	v_cndmask_b32_dpp v16, v38, v40, vcc quad_perm:[2,3,0,1] row_mask:0xf bank_mask:0xf
	v_cndmask_b32_dpp v17, v39, v41, vcc quad_perm:[2,3,0,1] row_mask:0xf bank_mask:0xf
	s_mov_b64 vcc, s[30:31]
	s_nop 1
	v_cndmask_b32_dpp v2, v28, v26, vcc quad_perm:[2,3,0,1] row_mask:0xf bank_mask:0xf
	v_cndmask_b32_dpp v3, v29, v27, vcc quad_perm:[2,3,0,1] row_mask:0xf bank_mask:0xf
	v_cndmask_b32_dpp v6, v32, v30, vcc quad_perm:[2,3,0,1] row_mask:0xf bank_mask:0xf
	v_cndmask_b32_dpp v7, v33, v31, vcc quad_perm:[2,3,0,1] row_mask:0xf bank_mask:0xf
	v_cndmask_b32_dpp v10, v36, v34, vcc quad_perm:[2,3,0,1] row_mask:0xf bank_mask:0xf
	v_cndmask_b32_dpp v11, v37, v35, vcc quad_perm:[2,3,0,1] row_mask:0xf bank_mask:0xf
	v_cndmask_b32_dpp v14, v40, v38, vcc quad_perm:[2,3,0,1] row_mask:0xf bank_mask:0xf
	v_cndmask_b32_dpp v15, v41, v39, vcc quad_perm:[2,3,0,1] row_mask:0xf bank_mask:0xf
	global_store_dwordx4 v45, v[2:5], s[20:21]
	global_store_dwordx4 v46, v[6:9], s[20:21]
	global_store_dwordx4 v47, v[10:13], s[20:21]
	global_store_dwordx4 v48, v[14:17], s[20:21]
	s_add_u32 s20, s20, 0x10000
	s_addc_u32 s21, s21, 0
	v_add_u32_e32 v44, 8, v44
	s_add_u32 s22, s22, 1
	s_waitcnt lgkmcnt(0)
	s_barrier
	s_cmp_lt_u32 s22, 0x81
	s_cbranch_scc1 .Ldn_c_loop
	s_branch .LBB0_1387
.Ldn_idle:
	s_mov_b32 s22, 0
	s_waitcnt lgkmcnt(0)
	s_barrier
.Ldn_i_loop:
	s_barrier
	s_add_u32 s22, s22, 1
	s_cmp_lt_u32 s22, 0x102
	s_cbranch_scc1 .Ldn_i_loop
	s_branch .LBB0_1387
.Ldn_loader:
	v_add_u32_e32 v3, 0xffffff00, v2
	v_lshlrev_b32_e32 v4, 4, v3
	v_add_u32_e32 v187, 0x800, v4
	s_lshl_b32 s9, s5, 12
	v_add_u32_e32 v186, s9, v187
	v_add3_u32 v251, v195, v4, s9
	v_lshrrev_b32_e32 v5, 3, v3
	v_and_b32_e32 v6, 7, v3
	v_mul_u32_u24_e32 v5, 0x90, v5
	v_lshl_add_u32 v5, v6, 4, v5
	v_add_u32_e32 v250, v195, v5
	global_load_dwordx4 v[2:5], v187, s[12:13] offset:-2048
	global_load_dwordx4 v[6:9], v187, s[12:13] offset:2048
	global_load_dwordx4 v[10:13], v187, s[14:15] offset:-2048
	global_load_dwordx4 v[14:17], v187, s[14:15] offset:2048
	global_load_dwordx4 v[18:21], v186, s[16:17] offset:-2048
	global_load_dwordx4 v[22:25], v186, s[18:19] offset:-2048
	s_waitcnt vmcnt(0)
	ds_write_b128 v250, v[2:5] offset:0
	ds_write_b128 v250, v[6:9] offset:4608
	ds_write_b128 v250, v[10:13] offset:9216
	ds_write_b128 v250, v[14:17] offset:13824
	ds_write_b128 v251, v[18:21] offset:18432
	ds_write_b128 v251, v[22:25] offset:26624
	v_add_u32_e32 v158, 0x2000, v187
	v_add_u32_e32 v159, 0x2000, v186
	global_load_dwordx4 v[2:5], v158, s[12:13] offset:-2048
	global_load_dwordx4 v[6:9], v158, s[12:13] offset:2048
	global_load_dwordx4 v[10:13], v158, s[14:15] offset:-2048
	global_load_dwordx4 v[14:17], v158, s[14:15] offset:2048
	global_load_dwordx4 v[18:21], v159, s[16:17] offset:-2048
	global_load_dwordx4 v[22:25], v159, s[18:19] offset:-2048
	v_add_u32_e32 v158, 0x4000, v187
	v_add_u32_e32 v159, 0x4000, v186
	global_load_dwordx4 v[26:29], v158, s[12:13] offset:-2048
	global_load_dwordx4 v[30:33], v158, s[12:13] offset:2048
	global_load_dwordx4 v[34:37], v158, s[14:15] offset:-2048
	global_load_dwordx4 v[38:41], v158, s[14:15] offset:2048
	global_load_dwordx4 v[42:45], v159, s[16:17] offset:-2048
	global_load_dwordx4 v[46:49], v159, s[18:19] offset:-2048
	v_add_u32_e32 v158, 0x6000, v187
	v_add_u32_e32 v159, 0x6000, v186
	global_load_dwordx4 v[50:53], v158, s[12:13] offset:-2048
	global_load_dwordx4 v[54:57], v158, s[12:13] offset:2048
	global_load_dwordx4 v[58:61], v158, s[14:15] offset:-2048
	global_load_dwordx4 v[62:65], v158, s[14:15] offset:2048
	global_load_dwordx4 v[66:69], v159, s[16:17] offset:-2048
	global_load_dwordx4 v[70:73], v159, s[18:19] offset:-2048
	s_mov_b32 s23, 3
	s_mov_b32 s22, 0
	s_waitcnt lgkmcnt(0)
	s_barrier
.Ldn_l_loop:
	s_sleep 3
	s_waitcnt vmcnt(12)
	ds_write_b128 v250, v[2:5] offset:34816
	ds_write_b128 v250, v[6:9] offset:39424
	ds_write_b128 v250, v[10:13] offset:44032
	ds_write_b128 v250, v[14:17] offset:48640
	ds_write_b128 v251, v[18:21] offset:53248
	ds_write_b128 v251, v[22:25] offset:61440
	s_add_u32 s23, s23, 1
	s_min_u32 s24, s23, 0x101
	s_lshl_b32 s24, s24, 13
	v_add_u32_e32 v158, s24, v187
	v_add_u32_e32 v159, s24, v186
	global_load_dwordx4 v[2:5], v158, s[12:13] offset:-2048
	global_load_dwordx4 v[6:9], v158, s[12:13] offset:2048
	global_load_dwordx4 v[10:13], v158, s[14:15] offset:-2048
	global_load_dwordx4 v[14:17], v158, s[14:15] offset:2048
	global_load_dwordx4 v[18:21], v159, s[16:17] offset:-2048
	global_load_dwordx4 v[22:25], v159, s[18:19] offset:-2048
	s_waitcnt lgkmcnt(0)
	s_barrier
	s_sleep 3
	s_waitcnt vmcnt(12)
	ds_write_b128 v250, v[26:29] offset:0
	ds_write_b128 v250, v[30:33] offset:4608
	ds_write_b128 v250, v[34:37] offset:9216
	ds_write_b128 v250, v[38:41] offset:13824
	ds_write_b128 v251, v[42:45] offset:18432
	ds_write_b128 v251, v[46:49] offset:26624
	s_add_u32 s23, s23, 1
	s_min_u32 s24, s23, 0x101
	s_lshl_b32 s24, s24, 13
	v_add_u32_e32 v158, s24, v187
	v_add_u32_e32 v159, s24, v186
	global_load_dwordx4 v[26:29], v158, s[12:13] offset:-2048
	global_load_dwordx4 v[30:33], v158, s[12:13] offset:2048
	global_load_dwordx4 v[34:37], v158, s[14:15] offset:-2048
	global_load_dwordx4 v[38:41], v158, s[14:15] offset:2048
	global_load_dwordx4 v[42:45], v159, s[16:17] offset:-2048
	global_load_dwordx4 v[46:49], v159, s[18:19] offset:-2048
	s_waitcnt lgkmcnt(0)
	s_barrier
	s_sleep 3
	s_waitcnt vmcnt(12)
	ds_write_b128 v250, v[50:53] offset:34816
	ds_write_b128 v250, v[54:57] offset:39424
	ds_write_b128 v250, v[58:61] offset:44032
	ds_write_b128 v250, v[62:65] offset:48640
	ds_write_b128 v251, v[66:69] offset:53248
	ds_write_b128 v251, v[70:73] offset:61440
	s_add_u32 s23, s23, 1
	s_min_u32 s24, s23, 0x101
	s_lshl_b32 s24, s24, 13
	v_add_u32_e32 v158, s24, v187
	v_add_u32_e32 v159, s24, v186
	global_load_dwordx4 v[50:53], v158, s[12:13] offset:-2048
	global_load_dwordx4 v[54:57], v158, s[12:13] offset:2048
	global_load_dwordx4 v[58:61], v158, s[14:15] offset:-2048
	global_load_dwordx4 v[62:65], v158, s[14:15] offset:2048
	global_load_dwordx4 v[66:69], v159, s[16:17] offset:-2048
	global_load_dwordx4 v[70:73], v159, s[18:19] offset:-2048
	s_waitcnt lgkmcnt(0)
	s_barrier
	s_sleep 3
	s_waitcnt vmcnt(12)
	ds_write_b128 v250, v[2:5] offset:0
	ds_write_b128 v250, v[6:9] offset:4608
	ds_write_b128 v250, v[10:13] offset:9216
	ds_write_b128 v250, v[14:17] offset:13824
	ds_write_b128 v251, v[18:21] offset:18432
	ds_write_b128 v251, v[22:25] offset:26624
	s_add_u32 s23, s23, 1
	s_min_u32 s24, s23, 0x101
	s_lshl_b32 s24, s24, 13
	v_add_u32_e32 v158, s24, v187
	v_add_u32_e32 v159, s24, v186
	global_load_dwordx4 v[2:5], v158, s[12:13] offset:-2048
	global_load_dwordx4 v[6:9], v158, s[12:13] offset:2048
	global_load_dwordx4 v[10:13], v158, s[14:15] offset:-2048
	global_load_dwordx4 v[14:17], v158, s[14:15] offset:2048
	global_load_dwordx4 v[18:21], v159, s[16:17] offset:-2048
	global_load_dwordx4 v[22:25], v159, s[18:19] offset:-2048
	s_waitcnt lgkmcnt(0)
	s_barrier
	s_sleep 3
	s_waitcnt vmcnt(12)
	ds_write_b128 v250, v[26:29] offset:34816
	ds_write_b128 v250, v[30:33] offset:39424
	ds_write_b128 v250, v[34:37] offset:44032
	ds_write_b128 v250, v[38:41] offset:48640
	ds_write_b128 v251, v[42:45] offset:53248
	ds_write_b128 v251, v[46:49] offset:61440
	s_add_u32 s23, s23, 1
	s_min_u32 s24, s23, 0x101
	s_lshl_b32 s24, s24, 13
	v_add_u32_e32 v158, s24, v187
	v_add_u32_e32 v159, s24, v186
	global_load_dwordx4 v[26:29], v158, s[12:13] offset:-2048
	global_load_dwordx4 v[30:33], v158, s[12:13] offset:2048
	global_load_dwordx4 v[34:37], v158, s[14:15] offset:-2048
	global_load_dwordx4 v[38:41], v158, s[14:15] offset:2048
	global_load_dwordx4 v[42:45], v159, s[16:17] offset:-2048
	global_load_dwordx4 v[46:49], v159, s[18:19] offset:-2048
	s_waitcnt lgkmcnt(0)
	s_barrier
	s_add_u32 s22, s22, 1
	s_sleep 3
	s_waitcnt vmcnt(12)
	ds_write_b128 v250, v[50:53] offset:0
	ds_write_b128 v250, v[54:57] offset:4608
	ds_write_b128 v250, v[58:61] offset:9216
	ds_write_b128 v250, v[62:65] offset:13824
	ds_write_b128 v251, v[66:69] offset:18432
	ds_write_b128 v251, v[70:73] offset:26624
	s_add_u32 s23, s23, 1
	s_min_u32 s24, s23, 0x101
	s_lshl_b32 s24, s24, 13
	v_add_u32_e32 v158, s24, v187
	v_add_u32_e32 v159, s24, v186
	global_load_dwordx4 v[50:53], v158, s[12:13] offset:-2048
	global_load_dwordx4 v[54:57], v158, s[12:13] offset:2048
	global_load_dwordx4 v[58:61], v158, s[14:15] offset:-2048
	global_load_dwordx4 v[62:65], v158, s[14:15] offset:2048
	global_load_dwordx4 v[66:69], v159, s[16:17] offset:-2048
	global_load_dwordx4 v[70:73], v159, s[18:19] offset:-2048
	s_waitcnt lgkmcnt(0)
	s_barrier
	s_cmp_lt_u32 s22, 43
	s_cbranch_scc1 .Ldn_l_loop
	s_branch .LBB0_1387
